# P1 full-line store transform + static s_setprio 1 for waves 0-3 during attention
# baseline (speedup 1.0000x reference)
; __global__ void __launch_bounds__(NWAVES * 64, 2) skel_fwd(Args args) {
;     ...
;         {
;             const bool bal = (F.G == 256);
;             const int x = vcu >> 5, j = vcu & 31, s = j & 7, srnd = 4 * ((vcu >> 3) & 3);
;             const int nU = bal ? (PROBE_DUP == 4 ? 32 : 16) : (4096 + F.G - 1) / F.G;
;             for (int u = 0; u < nU; ++u) {
;                 const int si = bal ? vcu : vcu + u * F.G;
;                 if (bal ? (u == srnd || (PROBE_DUP == 3 && u == srnd + 1)) : (si < 256)) attn_unit<true>(F, si >> 3, si & 7, 0, 0.f, 0.f);
.LBB0_446:
	s_cmp_lt_i32 s62, 1
	s_cbranch_scc1 .LBB0_532
	s_cmp_ge_u32 s97, 4
	s_cbranch_scc1 .Lprio_done
	s_setprio 1
